# static priority: s_setprio 1 for the second-dispatched wave half (waves 4-7) for the whole attention phase, reset to 0 at its end
# baseline (speedup 1.0000x reference)
; DI unsigned pk2(float a, float b) { f32x2 v = {a, b}; return __builtin_bit_cast(unsigned, __builtin_convertvector(v, bf2_t)); }
; DI float bflo(unsigned u) { return __uint_as_float(u << 16); }
; DI float bfhi(unsigned u) { return __uint_as_float(u & 0xffff0000u); }
; DI int vhalf() { return __builtin_amdgcn_readfirstlane((int)(threadIdx.x >> 8)); }
; DI unsigned xb_xcc_id() { return (unsigned)__builtin_amdgcn_readfirstlane((int)(__builtin_amdgcn_s_getreg((3 << 11) | 20) & 0xFu)); }
;     ...
;     bf16_t* yrow = yb + (size_t)(32 * w + r) * 1024 + 4 * h;
;     const bf16_t* grow = gt + (size_t)(32 * w + r) * 1024 + 4 * h;
;     u32x2 gv[2][4];
; #pragma unroll
;     for (int nt = 0; nt < 2; ++nt)
; #pragma unroll
;         for (int qd = 0; qd < 4; ++qd) gv[nt][qd] = *(const u32x2*)(grow + 32 * nt + 8 * qd);
; #pragma unroll
;     for (int nt = 0; nt < 2; ++nt)
; #pragma unroll
;         for (int qd = 0; qd < 4; ++qd) {
;             const u32x2 g = gv[nt][qd];
;             const f32x16& o = nt ? o1 : o0;
;             u32x2 v;
;             v.x = pk2(o[4 * qd] * bflo(g.x), o[4 * qd + 1] * bfhi(g.x));
;             v.y = pk2(o[4 * qd + 2] * bflo(g.y), o[4 * qd + 3] * bfhi(g.y));
;             *(u32x2*)(yrow + 32 * nt + 8 * qd) = v;
;         }
; DI void phase3(const Params& p, int l, unsigned char* smem, unsigned char* smem0) {
;     unsigned char* ws = p.ws; asm volatile("" : "+s"(ws));
;     unsigned* cnt = (unsigned*)(ws + O_CNT) + l * 8;
;     int* s_item = (int*)(smem0 + SMEM_ITEM);
;     const bf16_t* GATE = (const bf16_t*)(ws + O_GATE);
;     bf16_t* YBo = (bf16_t*)(ws + O_YB);
;     const int myx = (int)(xb_xcc_id() & 7u), hf = vhalf();
;     int vict = 0;
.LBB0_708:
	s_movk_i32 s85, 0xc0
	s_or_b64 exec, exec, s[36:37]
	s_lshl_b32 s48, s44, 3
	s_mov_b64 s[4:5], s[76:77]
	s_lshl_b64 s[6:7], s[48:49], 2
	s_waitcnt lgkmcnt(0)
	s_barrier
	s_add_u32 s3, s4, s6
	s_addc_u32 s6, s5, s7
	s_add_u32 s46, s3, 0x1a4c0000
	s_addc_u32 s47, s6, 0
	s_add_u32 s69, s4, 0x11080000
	s_addc_u32 s60, s5, 0
	s_add_u32 s61, s4, 0x1a4c3900
	v_readfirstlane_b32 s3, v214
	s_addc_u32 s70, s5, 0
	s_lshr_b32 s6, s3, 8
	s_lshl_b32 s72, s6, 3
	s_add_u32 s73, s4, 0x10080000
	s_mov_b32 s89, s74
	s_addc_u32 s74, s5, 0
	s_add_u32 s75, s4, 0x19f80000
	s_addc_u32 s87, s5, 0
	s_add_u32 s62, s4, 0x1a000000
	s_addc_u32 s3, s5, 0
	s_add_u32 s0, s4, 0x15d00000
	v_writelane_b32 v254, s0, 58
	s_addc_u32 s0, s5, 0
	v_writelane_b32 v254, s0, 59
	s_add_u32 s0, s4, 0x17500000
	v_writelane_b32 v254, s0, 60
	s_addc_u32 s0, s5, 0
	v_writelane_b32 v254, s0, 61
	s_add_u32 s0, s4, 0x18d00000
	v_writelane_b32 v254, s0, 62
	s_addc_u32 s0, s5, 0
	v_writelane_b32 v254, s0, 63
	s_add_u32 s0, s4, 0xa080000
	s_getreg_b32 s71, hwreg(HW_REG_XCC_ID, 0, 4)
	v_writelane_b32 v255, s0, 0
	s_addc_u32 s0, s5, 0
	v_writelane_b32 v255, s0, 1
	s_add_u32 s0, s4, 0xb080000
	v_writelane_b32 v255, s0, 2
	s_addc_u32 s0, s5, 0
	v_writelane_b32 v255, s0, 3
	s_add_u32 s0, s4, 0xc080000
	v_writelane_b32 v255, s0, 4
	s_addc_u32 s0, s5, 0
	s_lshl_b32 s6, s6, 4
	v_writelane_b32 v255, s0, 5
	s_add_i32 s0, s6, 0x12280
	v_writelane_b32 v255, s0, 6
	s_add_u32 s0, s4, 0xd080000
	v_writelane_b32 v255, s0, 7
	s_addc_u32 s0, s5, 0
	v_writelane_b32 v255, s0, 8
	s_add_u32 s0, s4, 0xe080000
	v_writelane_b32 v255, s0, 9
	s_addc_u32 s0, s5, 0
	v_writelane_b32 v255, s0, 10
	s_add_u32 s0, s4, 0xf080000
	v_writelane_b32 v255, s0, 11
	s_addc_u32 s0, s5, 0
	v_writelane_b32 v255, s0, 12
	s_add_u32 s0, s4, 0x19d00000
	v_writelane_b32 v255, s0, 13
	s_addc_u32 s0, s5, 0
	v_writelane_b32 v255, s0, 14
	s_add_u32 s0, s4, 0x1a4c0100
	v_writelane_b32 v255, s0, 15
	s_addc_u32 s0, s5, 0
	s_add_u32 s52, s4, 0x1a000080
	s_addc_u32 s53, s5, 0
	s_add_u32 s54, s4, 0x19f82000
	v_writelane_b32 v255, s0, 16
	s_addc_u32 s55, s5, 0
	v_mov_b32_e32 v124, 0
	s_cmp_eq_u32 s72, 0
	s_cbranch_scc1 .Lp3_prio_skip
	s_setprio 1
.Lp3_prio_skip:
	s_branch .LBB0_712
.LBB0_709:
	s_mov_b32 s57, s49
	s_lshl_b64 s[4:5], s[94:95], 11
	s_lshl_b64 s[6:7], s[56:57], 24
	s_or_b64 s[4:5], s[4:5], s[6:7]
	s_add_u32 s6, s69, s4
	s_addc_u32 s7, s60, s5
	s_lshl_b32 s8, s79, 7
	s_add_u32 s6, s6, s8
	s_addc_u32 s7, s7, 0
	v_lshlrev_b64 v[42:43], 11, v[100:101]
	v_lshl_add_u64 v[34:35], s[6:7], 0, v[42:43]
	v_lshlrev_b32_e32 v0, 1, v106
	v_lshl_add_u64 v[34:35], v[34:35], 0, v[0:1]
	global_load_dwordx2 v[44:45], v[34:35], off offset:512
	global_load_dwordx2 v[46:47], v[34:35], off offset:528
	global_load_dwordx2 v[48:49], v[34:35], off offset:544
	global_load_dwordx2 v[50:51], v[34:35], off offset:560
	global_load_dwordx2 v[40:41], v[34:35], off offset:576
	global_load_dwordx2 v[38:39], v[34:35], off offset:592
	global_load_dwordx2 v[36:37], v[34:35], off offset:608
	s_nop 0
	global_load_dwordx2 v[34:35], v[34:35], off offset:624
	s_add_u32 s4, s61, s4
	s_addc_u32 s5, s70, s5
	s_add_u32 s4, s4, s8
	s_addc_u32 s5, s5, 0
	v_lshl_add_u64 v[42:43], s[4:5], 0, v[42:43]
	v_lshl_add_u64 v[52:53], v[42:43], 0, v[0:1]
	s_mov_b64 s[4:5], 0x200
	v_lshl_add_u64 v[42:43], v[52:53], 0, s[4:5]
	s_mov_b32 s97, s0
	s_movk_i32 s90, 0x1000
	s_mov_b32 s88, 0x30000
	s_movk_i32 s92, 0x90
	s_mov_b32 s95, 0x7fffffe0
	s_movk_i32 s41, 0xffe0
	s_waitcnt vmcnt(0) lgkmcnt(0)
	v_lshlrev_b32_e32 v54, 16, v44
	v_and_b32_e32 v55, 0xffff0000, v44
	v_lshlrev_b32_e32 v44, 16, v45
	v_and_b32_e32 v45, 0xffff0000, v45
	v_pk_mul_f32 v[18:19], v[18:19], v[54:55]
	v_pk_mul_f32 v[20:21], v[20:21], v[44:45]
	v_cvt_pk_bf16_f32 v18, v18, v19
	v_cvt_pk_bf16_f32 v19, v20, v21
	global_store_dwordx2 v[52:53], v[18:19], off offset:512
	v_lshlrev_b32_e32 v18, 16, v46
	v_and_b32_e32 v19, 0xffff0000, v46
	v_lshlrev_b32_e32 v20, 16, v47
	v_and_b32_e32 v21, 0xffff0000, v47
	v_pk_mul_f32 v[18:19], v[22:23], v[18:19]
	v_pk_mul_f32 v[20:21], v[24:25], v[20:21]
	v_cvt_pk_bf16_f32 v18, v18, v19
	v_cvt_pk_bf16_f32 v19, v20, v21
	global_store_dwordx2 v[52:53], v[18:19], off offset:528
	v_lshlrev_b32_e32 v18, 16, v48
	v_and_b32_e32 v19, 0xffff0000, v48
	v_lshlrev_b32_e32 v20, 16, v49
	v_and_b32_e32 v21, 0xffff0000, v49
	v_pk_mul_f32 v[18:19], v[26:27], v[18:19]
	v_pk_mul_f32 v[20:21], v[28:29], v[20:21]
	v_cvt_pk_bf16_f32 v18, v18, v19
	v_cvt_pk_bf16_f32 v19, v20, v21
	global_store_dwordx2 v[52:53], v[18:19], off offset:544
	v_lshlrev_b32_e32 v18, 16, v50
	v_and_b32_e32 v19, 0xffff0000, v50
	v_lshlrev_b32_e32 v20, 16, v51
	v_and_b32_e32 v21, 0xffff0000, v51
	v_pk_mul_f32 v[18:19], v[30:31], v[18:19]
	v_pk_mul_f32 v[20:21], v[32:33], v[20:21]
	v_cvt_pk_bf16_f32 v18, v18, v19
	v_cvt_pk_bf16_f32 v19, v20, v21
	global_store_dwordx2 v[52:53], v[18:19], off offset:560

; DI unsigned xb_xcc_id() { return (unsigned)__builtin_amdgcn_readfirstlane((int)(__builtin_amdgcn_s_getreg((3 << 11) | 20) & 0xFu)); }
; DI void xcd_barrier(const XcdBarrier& b) {
;     asm volatile("s_waitcnt vmcnt(0)" ::: "memory");
;     __syncthreads();
;     if (threadIdx.x == 0) {
;         unsigned* bar = b.bar; asm volatile("" : "+s"(bar));
;         const unsigned bx = xb_xcc_id();
;         __builtin_amdgcn_s_waitcnt(0);
;         unsigned nloc = b.st[0], nx = b.st[1];
;         if (nloc == 0u) { xcd_barrier_complete(bar, bx, nloc, nx); b.st[0] = nloc; b.st[1] = nx; }
.LBB0_806:
	s_setprio 0
	s_waitcnt vmcnt(0)
	v_readlane_b32 s0, v253, 16
	v_readlane_b32 s1, v253, 17
	s_waitcnt lgkmcnt(0)
	s_barrier
	s_and_saveexec_b64 s[36:37], s[0:1]
	v_readlane_b32 s40, v254, 54
	s_mov_b32 s74, s89
	v_readlane_b32 s75, v254, 52
	s_movk_i32 s79, 0xc0
	v_readlane_b32 s41, v254, 55
	s_cbranch_execz .LBB0_850
	v_readlane_b32 s38, v253, 18
	v_readlane_b32 s39, v253, 19
	s_getreg_b32 s3, hwreg(HW_REG_XCC_ID, 0, 4)
	s_waitcnt vmcnt(0) expcnt(0) lgkmcnt(0)
	ds_read_b32 v2, v252
	ds_read_b32 v0, v229
	s_and_b32 s3, s3, 15
	s_waitcnt lgkmcnt(1)
	v_cmp_ne_u32_e32 vcc, 0, v2
	s_cbranch_vccnz .LBB0_821
	s_add_u32 s4, s38, 0x1000
	s_addc_u32 s5, s39, 0
	s_add_u32 s6, s38, 0x1100
	s_addc_u32 s7, s39, 0
	s_add_u32 s8, s38, 0x1200
	s_addc_u32 s9, s39, 0
	s_add_u32 s10, s38, 0x1300
	s_addc_u32 s11, s39, 0
	s_mov_b32 s30, 1
	s_mov_b64 s[12:13], 0
	s_branch .LBB0_811
